# weight conversion fully hidden: next-layer FFN1 weights converted by WGs>=192 at in-proj start, the rest by WGs>=128 before FFN1-up; standalone conversion phase and its grid sync removed
# baseline (speedup 1.0000x reference)
; #define EWA_REP for (int rep_ = 0; rep_ < 2; ++rep_)
; __global__ void __launch_bounds__(512, 2) mega_fwd(KArgs a) {
;     ...
;         if (l > 0) { { PH_VARS EWA_REP { CONV_LAYER(l); } } GSYNC(); }
.LBB0_1764:
	s_lshr_b32 s0, s1, 1
	v_writelane_b32 v252, s0, 25
	s_and_b32 s0, s1, 1
	s_cmp_eq_u32 s0, 0
	s_cselect_b64 s[12:13], -1, 0
	s_cmp_eq_u32 s0, 1
	s_cselect_b64 s[2:3], -1, 0
	s_cmp_eq_u32 s1, 0
	s_cselect_b64 s[6:7], -1, 0
	v_writelane_b32 v252, s1, 26
	s_and_b64 vcc, exec, s[6:7]
	s_cbranch_vccnz .LBB0_3143
	s_cmpk_lt_u32 s86, 0x80
	s_cbranch_scc1 .LBB0_3143
	v_writelane_b32 v254, 1, 40
.Lmy_conv_pre:
	s_mov_b64 s[0:1], s[88:89]
	v_mov_b32_e32 v1, v220
	s_movk_i32 s11, 0x70
	v_and_b32_e32 v4, 63, v1
	v_readfirstlane_b32 s4, v1
	s_waitcnt vmcnt(9)
	v_and_b32_e32 v70, 7, v1
	v_lshlrev_b32_e32 v5, 4, v4
	v_lshlrev_b32_e32 v2, 3, v1
	v_bfe_u32 v72, v1, 3, 3
	v_or_b32_e32 v1, 64, v4
	v_lshrrev_b32_e32 v75, 3, v1
	v_bitop3_b32 v77, v1, s11, v5 bitop3:0x48
	v_or_b32_e32 v1, 0xc0, v4
	v_lshrrev_b32_e32 v80, 3, v1
	v_bitop3_b32 v82, v1, s11, v5 bitop3:0x48
	v_or_b32_e32 v1, 0x140, v4
	v_lshrrev_b32_e32 v85, 3, v1
	v_bitop3_b32 v87, v1, s11, v5 bitop3:0x48
	v_or_b32_e32 v1, 0x1c0, v4
	s_waitcnt vmcnt(8)
	v_lshrrev_b32_e32 v90, 3, v1
	v_bitop3_b32 v92, v1, s11, v5 bitop3:0x48
	v_or_b32_e32 v1, 0x240, v4
	v_lshrrev_b32_e32 v95, 3, v1
	v_bitop3_b32 v97, v1, s11, v5 bitop3:0x48
	v_or_b32_e32 v1, 0x2c0, v4
	s_ashr_i32 s4, s4, 6
	v_readlane_b32 s5, v252, 0
	v_lshrrev_b32_e32 v100, 3, v1
	v_bitop3_b32 v102, v1, s11, v5 bitop3:0x48
	v_or_b32_e32 v1, 0x340, v4
	s_add_i32 s48, s4, s5
	s_lshl_b32 s4, s4, 14
	v_lshrrev_b32_e32 v105, 3, v1
	v_bitop3_b32 v107, v1, s11, v5 bitop3:0x48
	v_or_b32_e32 v1, 0x3c0, v4
	v_readlane_b32 s26, v252, 25
	s_add_i32 s10, s4, 0
	v_readlane_b32 s14, v252, 26
	v_readlane_b32 s15, v254, 40
	s_nop 1
	s_lshr_b32 s15, s15, 1
	s_add_i32 s14, s14, s15
	v_or_b32_e32 v78, 16, v72
	v_or_b32_e32 v83, 32, v72
	v_or_b32_e32 v88, 48, v72
	v_or_b32_e32 v93, 64, v72
	v_or_b32_e32 v98, 0x50, v72
	v_or_b32_e32 v103, 0x60, v72
	v_or_b32_e32 v108, 0x70, v72
	v_lshrrev_b32_e32 v110, 3, v1
	s_mul_i32 s16, s26, 0x1b2000
	s_mov_b32 s17, s68
	s_lshl_b32 s18, s26, 20
	s_mov_b32 s19, s68
	s_mul_i32 s20, s26, 0x2a8000
	s_mov_b32 s21, s68
	s_mul_i32 s22, s26, 0x30000
	s_mov_b32 s23, s68
	s_lshl_b32 s24, s26, 17
	s_mov_b32 s25, s68
	s_mul_i32 s26, s26, 0xc0000
	s_mov_b32 s27, s68
	s_mul_i32 s4, s14, 0x580000
	s_mov_b32 s5, s68
	s_lshl_b32 s8, s14, 10
	s_mov_b32 s9, s68
	s_waitcnt lgkmcnt(0)
	v_lshlrev_b32_e32 v3, 1, v4
	v_lshl_add_u32 v71, v4, 8, s10
	v_and_b32_e32 v2, 56, v2
	v_bitop3_b32 v73, v5, s11, v4 bitop3:0x48
	v_lshl_add_u32 v74, v72, 7, s10
	v_lshl_add_u32 v76, v75, 7, s10
	v_lshl_add_u32 v79, v78, 7, s10
	v_lshl_add_u32 v81, v80, 7, s10
	v_lshl_add_u32 v84, v83, 7, s10
	v_lshl_add_u32 v86, v85, 7, s10
	v_lshl_add_u32 v89, v88, 7, s10
	v_lshl_add_u32 v91, v90, 7, s10
	v_lshl_add_u32 v94, v93, 7, s10
	v_lshl_add_u32 v96, v95, 7, s10
	v_lshl_add_u32 v99, v98, 7, s10
	v_lshl_add_u32 v101, v100, 7, s10
	v_lshl_add_u32 v104, v103, 7, s10
	v_lshl_add_u32 v106, v105, 7, s10
	v_lshl_add_u32 v109, v108, 7, s10
	v_lshl_add_u32 v111, v110, 7, s10
	v_bitop3_b32 v112, v1, s11, v5 bitop3:0x48
	s_mul_i32 s10, s14, 0x2c0000
	s_mov_b32 s11, s68
	s_lshl_b32 s14, s14, 20
	s_mov_b32 s15, s68
	s_lshl_b64 s[16:17], s[16:17], 2
	s_lshl_b64 s[18:19], s[18:19], 2
	s_lshl_b64 s[20:21], s[20:21], 2
	s_lshl_b64 s[22:23], s[22:23], 2
	s_lshl_b64 s[24:25], s[24:25], 2
	s_lshl_b64 s[26:27], s[26:27], 2
	v_readlane_b32 s28, v254, 40
	s_nop 1
	s_cmp_eq_u32 s28, 2
	s_cbranch_scc1 .Lmy_conv_m2
	s_addk_i32 s48, 0x20
	s_branch .Lmy_conv_m1
.Lmy_conv_m2:
	s_addk_i32 s48, 0xfa00

.LBB0_1766:
	v_readlane_b32 s49, v254, 40
	s_nop 1
	s_cmp_eq_u32 s49, 2
	s_cbranch_scc0 .Lmy_conv_inc1
	s_addk_i32 s48, 0xfe00
.Lmy_conv_inc1:
	s_addk_i32 s48, 0x400
	s_cmp_eq_u32 s36, 53
	s_cbranch_scc0 .LBB0_3090
.LBB0_1767:
	v_readlane_b32 s28, v254, 40
	s_nop 1
	s_cmp_eq_u32 s28, 2
	s_cbranch_scc0 .Lmy_conv_disp
	s_cmpk_ge_i32 s48, 1056
	s_cbranch_scc1 .LBB0_3090

; __device__ __forceinline__ unsigned xb_ld(unsigned* p)              { return __hip_atomic_load(p, __ATOMIC_RELAXED, __HIP_MEMORY_SCOPE_AGENT); }
; __device__ __forceinline__ unsigned xb_add(unsigned* p, unsigned v) { return __hip_atomic_fetch_add(p, v, __ATOMIC_RELAXED, __HIP_MEMORY_SCOPE_AGENT); }
; #define XB_SPIN(cond, bar) do { unsigned _sp = 0; while (cond) { __builtin_amdgcn_s_sleep(1); \
;     if ((++_sp & 255u) == 0u) { if (xb_ld(&(bar)[XB_TMO])) break; if (_sp > XB_SPIN_CAP) { atomicAdd(&(bar)[XB_TMO], 1u); break; } } } } while (0)
; #define EWA_REP for (int rep_ = 0; rep_ < 2; ++rep_)
; __device__ __forceinline__ void xcd_barrier(const XcdBarrier& b) {
;     asm volatile("s_waitcnt vmcnt(0)" ::: "memory");
;     __syncthreads();
;     if (b.tid == 0u) {
;         unsigned* bar = b.bar;
;         __builtin_amdgcn_s_waitcnt(0);
;         unsigned nloc = b.st[0], nx = b.st[1];
;         if (nloc == 0u) { xcd_barrier_complete(bar, b.x, nloc, nx); b.st[0] = nloc; b.st[1] = nx; }
;         const unsigned old = xb_add(&bar[XB_XSUB(b.x)], 1u);
;         const unsigned gen = old / nloc;
;         if (old + 1u == (gen + 1u) * nloc) {
;             __builtin_amdgcn_fence(__ATOMIC_RELEASE, "agent");
;             asm volatile("s_waitcnt vmcnt(0)" ::: "memory");
;             const unsigned og = xb_add(&bar[XB_TOP], 1u);
;             const unsigned tg = og / nx;
;             if (og + 1u == (tg + 1u) * nx) xb_add(&bar[XB_TOPGEN], 1u);
;             else XB_SPIN(xb_ld(&bar[XB_TOPGEN]) == tg, bar);
;             __builtin_amdgcn_fence(__ATOMIC_ACQUIRE, "agent");
;             xb_add(&bar[XB_XGEN(b.x)], 1u);
;             asm volatile("s_waitcnt vmcnt(0)" ::: "memory");
;         } else {
;             XB_SPIN(xb_ld(&bar[XB_XGEN(b.x)]) == gen, bar);
;             __builtin_amdgcn_fence(__ATOMIC_ACQUIRE, "agent");
;             asm volatile("s_waitcnt vmcnt(0)" ::: "memory");
;         }
;     }
;     __syncthreads();
; }
; __global__ void __launch_bounds__(512, 2) mega_fwd(KArgs a) {
;     ...
;         if (l > 0) { { PH_VARS EWA_REP { CONV_LAYER(l); } } GSYNC(); }
.LBB0_3090:
	v_readlane_b32 s4, v254, 40
	s_nop 1
	s_cmp_eq_u32 s4, 2
	s_cbranch_scc1 .Lmy_conv3_done
	s_waitcnt lgkmcnt(0)
	s_barrier

; #define KA_DEF const __attribute__((address_space(4))) KArgs* ka_ = (const __attribute__((address_space(4))) KArgs*)__builtin_amdgcn_kernarg_segment_ptr(); asm volatile("" : "+s"(ka_));
; #define SSQ ((float*)WSP(WS_SSQ))
; __global__ void __launch_bounds__(512, 2) mega_fwd(KArgs a) {
;     ...
;         const int ldc = even ? EVEN_INP : ODD_INP;
;         { KA_DEF pg8::EpiBf16S E{RA, ldc, SSQ}; run_gemm(TIDX, lds, XB, Wl + WO_WIN, T_, ldc, 1024, E); }
.LBB0_3324:
	s_or_b64 exec, exec, s[0:1]
	s_mov_b64 s[0:1], s[88:89]
	s_waitcnt lgkmcnt(0)
	s_barrier
	s_cmpk_lt_u32 s86, 0xc0
	s_cbranch_scc1 .Lmy_inproj_go
	v_readlane_b32 vcc_lo, v252, 26
	s_nop 1
	s_cmp_eq_u32 vcc_lo, 3
	s_cbranch_scc1 .Lmy_inproj_go
	v_writelane_b32 v254, 2, 40
	s_branch .Lmy_conv_pre
.Lmy_conv3_done:
	s_waitcnt lgkmcnt(0)
	s_barrier
	s_mov_b64 s[0:1], s[88:89]
.Lmy_inproj_go:
	s_load_dwordx2 s[0:1], s[0:1], 0x100
	s_and_b64 s[4:5], s[12:13], exec
	s_movk_i32 s4, 0x700
	s_cselect_b32 s30, 0xb00, s4
	s_movk_i32 s4, 0x400
	s_waitcnt lgkmcnt(0)
	s_add_u32 s6, s0, 0x6000000
	s_addc_u32 s7, s1, 0
	s_add_u32 s8, s0, 0x2500000
	s_mov_b32 s5, s30
	s_movk_i32 s10, 0x4000
	s_addc_u32 s9, s1, 0
	s_ashr_i32 s11, s10, 31
	s_lshr_b32 s11, s11, 24
	s_add_i32 s10, s10, s11
	s_ashr_i32 s31, s10, 8
	s_ashr_i32 s10, s5, 31
	s_lshr_b32 s10, s10, 24
	s_add_i32 s5, s5, s10
	s_ashr_i32 s16, s5, 8
	s_mul_i32 s10, s16, s31
	v_mov_b32_e32 v14, v220
	s_cmp_ge_i32 s86, s10
	v_readfirstlane_b32 s22, v14
	s_cbranch_scc1 .LBB0_3353
	s_ashr_i32 s11, s10, 31
	s_lshr_b32 s5, s11, 29
	s_add_i32 s5, s10, s5
	s_ashr_i32 s34, s5, 3
	s_and_b32 s5, s5, -8
	s_sub_i32 s35, s10, s5
	s_add_i32 s36, s34, 1
	v_readlane_b32 s5, v252, 5
	s_cmp_ge_i32 s5, s35
	s_mov_b64 s[12:13], -1
	s_mul_i32 s37, s36, s35
	s_cbranch_scc0 .LBB0_3327
	v_readlane_b32 s5, v252, 5
	s_sub_i32 s5, s5, s35
	s_mul_i32 s5, s5, s34
	s_add_i32 s17, s5, s37
	s_mov_b64 s[12:13], 0
